# grid barrier: the mid (n/2-th) arriver of each XCD starts an early L2 write-back
# baseline (speedup 1.0000x reference)
; __device__ __forceinline__ unsigned xb_ld(unsigned* p)              { return __hip_atomic_load(p, __ATOMIC_RELAXED, __HIP_MEMORY_SCOPE_AGENT); }
; __device__ __forceinline__ unsigned xb_add(unsigned* p, unsigned v) { return __hip_atomic_fetch_add(p, v, __ATOMIC_RELAXED, __HIP_MEMORY_SCOPE_AGENT); }
; #define XB_SPIN(cond, bar) do { unsigned _sp = 0; while (cond) { __builtin_amdgcn_s_sleep(1); \
;     if ((++_sp & 255u) == 0u) { if (xb_ld(&(bar)[XB_TMO])) break; if (_sp > XB_SPIN_CAP) { atomicAdd(&(bar)[XB_TMO], 1u); break; } } } } while (0)
; __device__ __forceinline__ void xcd_barrier(const XcdBarrier& b) {
;     ...
;         unsigned nloc = b.st[0], nx = b.st[1];
;         if (nloc == 0u) { xcd_barrier_complete(bar, b.x, nloc, nx); b.st[0] = nloc; b.st[1] = nx; }
;         const unsigned old = xb_add(&bar[XB_XSUB(b.x)], 1u);
;         const unsigned gen = old / nloc;
;         if (old + 1u == (gen + 1u) * nloc) {
;             __builtin_amdgcn_fence(__ATOMIC_RELEASE, "agent");
;             asm volatile("s_waitcnt vmcnt(0)" ::: "memory");
;             const unsigned og = xb_add(&bar[XB_TOP], 1u);
;             const unsigned tg = og / nx;
;             if (og + 1u == (tg + 1u) * nx) xb_add(&bar[XB_TOPGEN], 1u);
;             else XB_SPIN(xb_ld(&bar[XB_TOPGEN]) == tg, bar);
.LBB0_36:
	s_or_b64 exec, exec, s[10:11]
	v_cvt_f32_u32_e32 v10, v4
	s_waitcnt vmcnt(0)
	v_readfirstlane_b32 s2, v5
	buffer_inv sc1
	v_sub_u32_e32 v5, 0, v4
	v_rcp_iflag_f32_e32 v10, v10
	v_add_u32_e32 v11, s2, v1
	v_mul_f32_e32 v10, 0x4f7ffffe, v10
	v_cvt_u32_f32_e32 v10, v10
	v_mul_lo_u32 v1, v5, v10
	v_mul_hi_u32 v1, v10, v1
	v_add_u32_e32 v1, v10, v1
	v_mul_hi_u32 v1, v11, v1
	v_mul_lo_u32 v5, v1, v4
	v_sub_u32_e32 v5, v11, v5
	v_add_u32_e32 v10, 1, v1
	v_cmp_ge_u32_e32 vcc, v5, v4
	s_nop 1
	v_cndmask_b32_e32 v1, v1, v10, vcc
	v_sub_u32_e32 v10, v5, v4
	v_cndmask_b32_e32 v5, v5, v10, vcc
	v_add_u32_e32 v10, 1, v1
	v_cmp_ge_u32_e32 vcc, v5, v4
	v_add_u32_e32 v5, 1, v11
	s_nop 0
	v_cndmask_b32_e32 v1, v1, v10, vcc
	v_mul_lo_u32 v10, v4, v1
	v_add_u32_e32 v4, v10, v4
	v_cmp_ne_u32_e32 vcc, v5, v4
	s_and_saveexec_b64 s[2:3], vcc
	s_xor_b64 s[8:9], exec, s[2:3]
	s_cbranch_execz .LBB0_50
	v_sub_u32_e32 v10, v4, v10
	v_lshrrev_b32_e32 v10, 1, v10
	v_add_u32_e32 v10, v10, v5
	v_cmp_eq_u32_e32 vcc, v10, v4
	s_cbranch_vccz .Lpf_skip
	buffer_wbl2 sc1
